# P0a: workgroups 192-255 touch the w_mod slices of same-XCD GEMV workgroups while those stage their inputs
# baseline (speedup 1.0000x reference)
.LBB0_54:
	s_or_b64 exec, exec, s[4:5]
	s_branch .LBB0_55
.Lwm_0:
	s_load_dwordx2 s[4:5], s[78:79], 0x20
	s_sub_u32 s8, s2, 0xc0
	s_lshr_b32 s9, s8, 3
	s_and_b32 s8, s8, 7
	s_mul_i32 s9, s9, 3
	v_lshrrev_b32_e32 v176, 6, v224
	v_and_b32_e32 v177, 63, v224
	v_lshl_add_u32 v176, v176, 7, v177
	v_mul_u32_u24_e32 v176, 0x6000, v176
	v_add_u32_e32 v178, 0x180000, v176
	s_waitcnt lgkmcnt(0)
	s_add_u32 s10, s9, 0
	s_lshl_b32 s10, s10, 3
	s_add_u32 s10, s10, s8
	s_cmp_ge_u32 s10, 0x60
	s_cselect_b32 s11, 0x60, 0
	s_sub_u32 s10, s10, s11
	s_lshl_b32 s10, s10, 8
	s_lshl_b32 s11, s11, 18
	s_add_u32 s6, s4, s10
	s_addc_u32 s7, s5, 0
	s_add_u32 s6, s6, s11
	s_addc_u32 s7, s7, 0
	global_load_dword v184, v176, s[6:7]
	global_load_dword v184, v176, s[6:7] offset:64
	global_load_dword v184, v176, s[6:7] offset:128
	global_load_dword v184, v176, s[6:7] offset:192
	global_load_dword v184, v178, s[6:7]
	global_load_dword v184, v178, s[6:7] offset:64
	global_load_dword v184, v178, s[6:7] offset:128
	global_load_dword v184, v178, s[6:7] offset:192
	s_add_u32 s10, s9, 1
	s_lshl_b32 s10, s10, 3
	s_add_u32 s10, s10, s8
	s_cmp_ge_u32 s10, 0x60
	s_cselect_b32 s11, 0x60, 0
	s_sub_u32 s10, s10, s11
	s_lshl_b32 s10, s10, 8
	s_lshl_b32 s11, s11, 18
	s_add_u32 s6, s4, s10
	s_addc_u32 s7, s5, 0
	s_add_u32 s6, s6, s11
	s_addc_u32 s7, s7, 0
	global_load_dword v184, v176, s[6:7]
	global_load_dword v184, v176, s[6:7] offset:64
	global_load_dword v184, v176, s[6:7] offset:128
	global_load_dword v184, v176, s[6:7] offset:192
	global_load_dword v184, v178, s[6:7]
	global_load_dword v184, v178, s[6:7] offset:64
	global_load_dword v184, v178, s[6:7] offset:128
	global_load_dword v184, v178, s[6:7] offset:192
	s_add_u32 s10, s9, 2
	s_lshl_b32 s10, s10, 3
	s_add_u32 s10, s10, s8
	s_cmp_ge_u32 s10, 0x60
	s_cselect_b32 s11, 0x60, 0
	s_sub_u32 s10, s10, s11
	s_lshl_b32 s10, s10, 8
	s_lshl_b32 s11, s11, 18
	s_add_u32 s6, s4, s10
	s_addc_u32 s7, s5, 0
	s_add_u32 s6, s6, s11
	s_addc_u32 s7, s7, 0
	global_load_dword v184, v176, s[6:7]
	global_load_dword v184, v176, s[6:7] offset:64
	global_load_dword v184, v176, s[6:7] offset:128
	global_load_dword v184, v176, s[6:7] offset:192
	global_load_dword v184, v178, s[6:7]
	global_load_dword v184, v178, s[6:7] offset:64
	global_load_dword v184, v178, s[6:7] offset:128
	global_load_dword v184, v178, s[6:7] offset:192
	s_waitcnt vmcnt(0)
